# NSA selected loop: batch K ds_reads before QK MFMAs, prefetch V ds_reads before PV MFMAs (counted lgkmcnt)
# speedup vs baseline: 1.0194x; 1.0194x over previous
; #define MFMA32(a, b, c) __builtin_amdgcn_mfma_f32_32x32x16_bf16((a), (b), (c), 0, 0, 0)
; DI void qk_tile(const u16* Ks, const bf16x8* qf, f32x16* s, int rl, int hh) {
; #pragma unroll
;   for (int kb = 0; kb < 2; ++kb) {
; #pragma unroll
;     for (int i = 0; i < 16; ++i) s[kb][i] = 0.f;
; #pragma unroll
;     for (int ks = 0; ks < 4; ++ks) {
;       bf16x8 a = *(const bf16x8*)(Ks + (kb * 32 + rl) * KVS + ks * 16 + hh * 8);
;       s[kb] = MFMA32(a, qf[ks], s[kb]);
;     }
;   }
; }
; DI void online_softmax(f32x16* s, uint32_t vm, float& m, float& l, f32x16* o) {
;   const unsigned long long ball = __ballot(vm == 0xffffffffu), bnone = __ballot(vm == 0u);
;   if (ball == ~0ull) osm<0>(s, vm, m, l, o);
;   else if ((ball | bnone) == ~0ull) osm<1>(s, vm, m, l, o);
;   else osm<2>(s, vm, m, l, o);
; }
.LBB0_1684:
	s_or_b64 exec, exec, s[12:13]
	v_cmp_ne_u32_e64 s[10:11], 0, v96
	s_mov_b64 vcc, s[10:11]
	s_cbranch_vccz .LBB0_1694
	s_mul_i32 s3, s29, 0x4800
	v_or_b32_e32 v250, s3, v0
	v_lshl_add_u32 v97, v246, 1, v250
	ds_read_b128 v[98:101], v97
	ds_read_b128 v[102:105], v97 offset:32
	ds_read_b128 v[106:109], v97 offset:64
	ds_read_b128 v[128:131], v97 offset:96
	ds_read_b128 v[80:83], v97 offset:4608
	ds_read_b128 v[132:135], v97 offset:4640
	ds_read_b128 v[136:139], v97 offset:4672
	ds_read_b128 v[140:143], v97 offset:4704
	v_cmp_eq_u32_e32 vcc, -1, v96
	v_cmp_eq_u32_e64 s[12:13], 0, v96
	s_cmp_lg_u64 vcc, -1
	s_waitcnt lgkmcnt(7)
	v_mfma_f32_32x32x16_bf16 v[112:127], v[98:101], v[2:5], 0
	s_waitcnt lgkmcnt(6)
	v_mfma_f32_32x32x16_bf16 v[112:127], v[102:105], v[176:179], v[112:127]
	s_waitcnt lgkmcnt(5)
	v_mfma_f32_32x32x16_bf16 v[112:127], v[106:109], v[180:183], v[112:127]
	s_waitcnt lgkmcnt(4)
	v_mfma_f32_32x32x16_bf16 v[112:127], v[128:131], v[184:187], v[112:127]
	s_waitcnt lgkmcnt(3)
	v_mfma_f32_32x32x16_bf16 v[80:95], v[80:83], v[2:5], 0
	s_waitcnt lgkmcnt(2)
	v_mfma_f32_32x32x16_bf16 v[80:95], v[132:135], v[176:179], v[80:95]
	s_waitcnt lgkmcnt(1)
	v_mfma_f32_32x32x16_bf16 v[80:95], v[136:139], v[180:183], v[80:95]
	s_waitcnt lgkmcnt(0)
	v_mfma_f32_32x32x16_bf16 v[80:95], v[140:143], v[184:187], v[80:95]
	s_cbranch_scc0 .LBB0_1758
	s_or_b64 s[4:5], s[12:13], vcc
	s_cmp_lg_u64 s[4:5], -1
	s_cbranch_scc0 .LBB0_1762
	v_and_b32_e32 v97, 1, v96
	v_cmp_eq_u32_e32 vcc, 1, v97
	v_and_b32_e32 v98, 2, v96
	v_and_b32_e32 v100, 4, v96
	v_cndmask_b32_e32 v97, v204, v112, vcc
	v_cmp_ne_u32_e32 vcc, 0, v98
	v_and_b32_e32 v101, 8, v96
	v_and_b32_e32 v102, 16, v96
	v_cndmask_b32_e32 v98, v204, v113, vcc
	v_cmp_ne_u32_e32 vcc, 0, v100
	v_and_b32_e32 v103, 32, v96
	v_and_b32_e32 v104, 64, v96
	v_cndmask_b32_e32 v100, v204, v114, vcc
	v_cmp_ne_u32_e32 vcc, 0, v101
	v_and_b32_e32 v105, 0x80, v96
	v_and_b32_e32 v106, 0x100, v96
	v_cndmask_b32_e32 v101, v204, v115, vcc
	v_cmp_ne_u32_e32 vcc, 0, v102
	v_and_b32_e32 v107, 0x200, v96
	v_and_b32_e32 v108, 0x400, v96
	v_cndmask_b32_e32 v102, v204, v116, vcc
	v_cmp_ne_u32_e32 vcc, 0, v103
	v_and_b32_e32 v109, 0x800, v96
	v_and_b32_e32 v110, 0x1000, v96
	v_cndmask_b32_e32 v103, v204, v117, vcc
	v_cmp_ne_u32_e32 vcc, 0, v104
	v_and_b32_e32 v111, 0x2000, v96
	v_and_b32_e32 v128, 0x4000, v96
	v_cndmask_b32_e32 v104, v204, v118, vcc
	v_cmp_ne_u32_e32 vcc, 0, v105
	v_and_b32_e32 v129, 0x8000, v96
	v_and_b32_e32 v130, 0x10000, v96
	v_cndmask_b32_e32 v105, v204, v119, vcc
	v_cmp_ne_u32_e32 vcc, 0, v106
	v_and_b32_e32 v131, 0x20000, v96
	v_and_b32_e32 v132, 0x40000, v96
	v_cndmask_b32_e32 v106, v204, v120, vcc
	v_cmp_ne_u32_e32 vcc, 0, v107
	v_max3_f32 v99, v97, s77, v98
	v_and_b32_e32 v133, 0x80000, v96
	v_cndmask_b32_e32 v107, v204, v121, vcc
	v_cmp_ne_u32_e32 vcc, 0, v108
	v_max3_f32 v99, v99, v100, v101
	v_and_b32_e32 v134, 0x100000, v96
	v_cndmask_b32_e32 v108, v204, v122, vcc
	v_cmp_ne_u32_e32 vcc, 0, v109
	v_max3_f32 v99, v99, v102, v103
	v_and_b32_e32 v135, 0x200000, v96
	v_cndmask_b32_e32 v109, v204, v123, vcc
	v_cmp_ne_u32_e32 vcc, 0, v110
	v_max3_f32 v99, v99, v104, v105
	v_and_b32_e32 v136, 0x400000, v96
	v_cndmask_b32_e32 v110, v204, v124, vcc
	v_cmp_ne_u32_e32 vcc, 0, v111
	v_max3_f32 v99, v99, v106, v107
	v_and_b32_e32 v137, 0x800000, v96
	v_cndmask_b32_e32 v111, v204, v125, vcc
	v_cmp_ne_u32_e32 vcc, 0, v128
	v_max3_f32 v99, v99, v108, v109
	v_and_b32_e32 v138, 0x1000000, v96
	v_cndmask_b32_e32 v128, v204, v126, vcc
	v_cmp_ne_u32_e32 vcc, 0, v129
	v_max3_f32 v99, v99, v110, v111
	v_and_b32_e32 v139, 0x2000000, v96
	v_cndmask_b32_e32 v129, v204, v127, vcc
	v_cmp_ne_u32_e32 vcc, 0, v130
	v_max3_f32 v99, v99, v128, v129
	v_and_b32_e32 v140, 0x4000000, v96
	v_cndmask_b32_e32 v130, v204, v80, vcc
	v_cmp_ne_u32_e32 vcc, 0, v131
	v_and_b32_e32 v141, 0x8000000, v96
	v_and_b32_e32 v142, 0x10000000, v96
	v_cndmask_b32_e32 v131, v204, v81, vcc
	v_cmp_ne_u32_e32 vcc, 0, v132
	v_max3_f32 v99, v99, v130, v131
	v_and_b32_e32 v143, 0x20000000, v96
	v_cndmask_b32_e32 v132, v204, v82, vcc
	v_cmp_ne_u32_e32 vcc, 0, v133
	v_and_b32_e32 v202, 2.0, v96
	s_nop 0
	v_cndmask_b32_e32 v133, v204, v83, vcc
	v_cmp_ne_u32_e32 vcc, 0, v134
	v_max3_f32 v99, v99, v132, v133
	s_nop 0
	v_cndmask_b32_e32 v134, v204, v84, vcc
	v_cmp_ne_u32_e32 vcc, 0, v135
	s_nop 1
	v_cndmask_b32_e32 v135, v204, v85, vcc
	v_cmp_ne_u32_e32 vcc, 0, v136
	v_max3_f32 v99, v99, v134, v135
	s_nop 0
	v_cndmask_b32_e32 v136, v204, v86, vcc
	v_cmp_ne_u32_e32 vcc, 0, v137
	s_nop 1
; DI float fexp2(float x) { return __builtin_amdgcn_exp2f(x); }
; template <int MODE>
; DI void osm(f32x16* s, uint32_t vm, float& m, float& l, f32x16* o) {
;   float mx = -1e30f;
; #pragma unroll
;   for (int kb = 0; kb < 2; ++kb)
; #pragma unroll
;     for (int i = 0; i < 16; ++i) {
;       if (MODE == 2) s[kb][i] = ((vm >> (kb * 16 + i)) & 1u) ? s[kb][i] : -1e30f;
;       mx = fmaxf(mx, s[kb][i]);
;     }
;   mx *= SCL2;
;   if (MODE == 1) mx = vm ? mx : -1e30f;
;   mx = xmax32(mx);
;   const float mn = fmaxf(m, mx);
;   const float alpha = fexp2(m - mn);
;   const bool rowok = (MODE == 1) ? (vm != 0u) : true;
;   const float mu = (rowok && mn > -1e29f) ? mn : 1e30f;
;   float rs = 0.f;
; #pragma unroll
;   for (int kb = 0; kb < 2; ++kb)
; #pragma unroll
;     for (int i = 0; i < 16; ++i) {
;       const float pv = fexp2(__builtin_fmaf(s[kb][i], SCL2, -mu));
;       s[kb][i] = pv;
;       rs += pv;
;     }
;   rs = xsum32(rs);
;   l = l * alpha + rs;
;   if (__ballot(mn > m) != 0ull) {
; #pragma unroll
;     for (int db = 0; db < 2; ++db)
; #pragma unroll
;       for (int i = 0; i < 16; ++i) o[db][i] *= alpha;
;   }
;   m = mn;
; }
	v_cndmask_b32_e32 v137, v204, v87, vcc
	v_cmp_ne_u32_e32 vcc, 0, v138
	v_max3_f32 v99, v99, v136, v137
	s_nop 0
	v_cndmask_b32_e32 v138, v204, v88, vcc
	v_cmp_ne_u32_e32 vcc, 0, v139
	s_nop 1
	v_cndmask_b32_e32 v139, v204, v89, vcc
	v_cmp_ne_u32_e32 vcc, 0, v140
	v_max3_f32 v99, v99, v138, v139
	s_nop 0
	v_cndmask_b32_e32 v140, v204, v90, vcc
	v_cmp_ne_u32_e32 vcc, 0, v141
	s_nop 1
	v_cndmask_b32_e32 v141, v204, v91, vcc
	v_cmp_ne_u32_e32 vcc, 0, v142
	v_max3_f32 v99, v99, v140, v141
	s_nop 0
	v_cndmask_b32_e32 v142, v204, v92, vcc
	v_cmp_ne_u32_e32 vcc, 0, v143
	s_nop 1
	v_cndmask_b32_e32 v143, v204, v93, vcc
	v_cmp_ne_u32_e32 vcc, 0, v202
	v_max3_f32 v99, v99, v142, v143
	s_nop 0
	v_cndmask_b32_e32 v202, v204, v94, vcc
	v_cmp_gt_i32_e32 vcc, 0, v96
	s_nop 1
	v_cndmask_b32_e32 v252, v204, v95, vcc
	v_max3_f32 v96, v99, v202, v252
	v_mul_f32_e32 v96, 0x3e38aa3b, v96
	v_mov_b32_e32 v99, v96
	s_nop 1
	v_permlane32_swap_b32_e32 v96, v99
	v_max3_f32 v251, v249, v96, v99
	v_cmp_lt_f32_e32 vcc, s1, v251
	v_sub_f32_e32 v253, v249, v251
	s_nop 0
	v_cndmask_b32_e64 v254, v204, -v251, vcc
	v_fmamk_f32 v96, v97, 0x3e38aa3b, v254
	v_exp_f32_e32 v96, v96
	v_fmamk_f32 v97, v98, 0x3e38aa3b, v254
	v_exp_f32_e32 v97, v97
	v_fmamk_f32 v98, v100, 0x3e38aa3b, v254
	v_exp_f32_e32 v98, v98
	v_fmamk_f32 v99, v101, 0x3e38aa3b, v254
	v_exp_f32_e32 v99, v99
	v_add_f32_e32 v100, 0, v96
	v_add_f32_e32 v100, v97, v100
	v_add_f32_e32 v100, v98, v100
	v_add_f32_e32 v229, v99, v100
	v_fmamk_f32 v100, v102, 0x3e38aa3b, v254
	v_exp_f32_e32 v100, v100
	v_fmamk_f32 v101, v103, 0x3e38aa3b, v254
	v_exp_f32_e32 v101, v101
	v_fmamk_f32 v102, v104, 0x3e38aa3b, v254
	v_exp_f32_e32 v102, v102
	v_fmamk_f32 v103, v105, 0x3e38aa3b, v254
	v_exp_f32_e32 v103, v103
	v_add_f32_e32 v104, v100, v229
	v_add_f32_e32 v104, v101, v104
	v_add_f32_e32 v104, v102, v104
	v_add_f32_e32 v229, v103, v104
	v_fmamk_f32 v104, v106, 0x3e38aa3b, v254
	v_exp_f32_e32 v104, v104
	v_fmamk_f32 v105, v107, 0x3e38aa3b, v254
	v_exp_f32_e32 v105, v105
	v_fmamk_f32 v106, v108, 0x3e38aa3b, v254
	v_exp_f32_e32 v106, v106
	v_fmamk_f32 v107, v109, 0x3e38aa3b, v254
	v_exp_f32_e32 v107, v107
	v_add_f32_e32 v108, v104, v229
	v_add_f32_e32 v108, v105, v108
	v_add_f32_e32 v108, v106, v108
	v_add_f32_e32 v229, v107, v108
	v_fmamk_f32 v108, v110, 0x3e38aa3b, v254
	v_exp_f32_e32 v108, v108
	v_fmamk_f32 v109, v111, 0x3e38aa3b, v254
	v_exp_f32_e32 v109, v109
	v_fmamk_f32 v110, v128, 0x3e38aa3b, v254
	v_exp_f32_e32 v110, v110
	v_fmamk_f32 v111, v129, 0x3e38aa3b, v254
	v_exp_f32_e32 v111, v111
	v_add_f32_e32 v128, v108, v229
	v_add_f32_e32 v128, v109, v128
	v_add_f32_e32 v128, v110, v128
	v_add_f32_e32 v229, v111, v128
	v_fmamk_f32 v128, v130, 0x3e38aa3b, v254
	v_exp_f32_e32 v128, v128
	v_fmamk_f32 v129, v131, 0x3e38aa3b, v254
	v_exp_f32_e32 v129, v129
	v_fmamk_f32 v130, v132, 0x3e38aa3b, v254
	v_exp_f32_e32 v130, v130
	v_fmamk_f32 v131, v133, 0x3e38aa3b, v254
	v_exp_f32_e32 v131, v131
	v_add_f32_e32 v132, v128, v229
	v_add_f32_e32 v132, v129, v132
	v_add_f32_e32 v132, v130, v132
	v_add_f32_e32 v229, v131, v132
	v_fmamk_f32 v132, v134, 0x3e38aa3b, v254
	v_exp_f32_e32 v132, v132
	v_fmamk_f32 v133, v135, 0x3e38aa3b, v254
	v_exp_f32_e32 v133, v133
	v_fmamk_f32 v134, v136, 0x3e38aa3b, v254
	v_exp_f32_e32 v134, v134
	v_fmamk_f32 v135, v137, 0x3e38aa3b, v254
	v_exp_f32_e32 v135, v135
	v_add_f32_e32 v136, v132, v229
	v_add_f32_e32 v136, v133, v136
	v_add_f32_e32 v136, v134, v136
	v_add_f32_e32 v229, v135, v136
	v_fmamk_f32 v136, v138, 0x3e38aa3b, v254
	v_exp_f32_e32 v136, v136
	v_fmamk_f32 v137, v139, 0x3e38aa3b, v254
	v_exp_f32_e32 v137, v137
	v_fmamk_f32 v138, v140, 0x3e38aa3b, v254
	v_exp_f32_e32 v138, v138
	v_fmamk_f32 v139, v141, 0x3e38aa3b, v254
	v_exp_f32_e32 v139, v139
	v_add_f32_e32 v140, v136, v229
	v_add_f32_e32 v140, v137, v140
	v_add_f32_e32 v140, v138, v140
	v_add_f32_e32 v229, v139, v140
	v_fmamk_f32 v140, v142, 0x3e38aa3b, v254
	v_exp_f32_e32 v140, v140
	v_fmamk_f32 v141, v143, 0x3e38aa3b, v254
	v_exp_f32_e32 v141, v141
	v_fmamk_f32 v142, v202, 0x3e38aa3b, v254
	v_exp_f32_e32 v142, v142
	v_fmac_f32_e32 v254, 0x3e38aa3b, v252
	v_exp_f32_e32 v143, v254
	v_add_f32_e32 v202, v140, v229
	v_add_f32_e32 v202, v141, v202
	v_add_f32_e32 v202, v142, v202
	v_add_f32_e32 v229, v143, v202
	v_exp_f32_e32 v202, v253
	v_mov_b32_e32 v252, v229
	s_nop 1
	v_permlane32_swap_b32_e32 v229, v252
	v_cmp_gt_f32_e32 vcc, v251, v249
	v_add_f32_e32 v252, v229, v252
	s_cmp_lg_u64 vcc, 0
	v_fmac_f32_e32 v252, v248, v202
	s_cselect_b64 s[12:13], -1, 0
	s_cbranch_execnz .LBB0_1689

; #define MFMA32(a, b, c) __builtin_amdgcn_mfma_f32_32x32x16_bf16((a), (b), (c), 0, 0, 0)
; DI void pv_tile(const u16* Vs, const f32x16* s, f32x16* o, int rl, int hh) {
; #pragma unroll
;   for (int kk = 0; kk < 4; ++kk) {
;     const int kb = kk >> 1, i0 = 8 * (kk & 1);
;     bf16x8 pf = pack8(s[kb][i0], s[kb][i0 + 1], s[kb][i0 + 2], s[kb][i0 + 3], s[kb][i0 + 4], s[kb][i0 + 5], s[kb][i0 + 6], s[kb][i0 + 7]);
; #pragma unroll
;     for (int db = 0; db < 2; ++db) {
;       const u16* vp = Vs + (db * 32 + rl) * KVS + kk * 16 + hh * 4;
;       s16x4 lo = *(const s16x4*)vp, hi = *(const s16x4*)(vp + 8);
;       bf16x8 a = __builtin_shufflevector(lo, hi, 0, 1, 2, 3, 4, 5, 6, 7);
;       o[db] = MFMA32(a, pf, o[db]);
;     }
;   }
; }
.LBB0_1693:
	s_nop 0
	v_lshlrev_b32_e32 v84, 1, v246
	v_add3_u32 v88, v250, v247, v84
	s_nop 2
	v_add_u32_e32 v89, 0x2000, v88
	v_add_u32_e32 v88, 0x3000, v88
	ds_read2_b64 v[112:115], v89 offset0:128 offset1:130
	ds_read2_b64 v[116:119], v88 offset0:192 offset1:194
	ds_read2_b64 v[120:123], v89 offset0:132 offset1:134
	ds_read2_b64 v[124:127], v88 offset0:196 offset1:198
	ds_read2_b64 v[84:87], v89 offset0:136 offset1:138
	ds_read2_b64 v[92:95], v88 offset0:200 offset1:202
	v_cvt_pk_bf16_f32 v80, v96, v97
	v_cvt_pk_bf16_f32 v81, v98, v99
	v_cvt_pk_bf16_f32 v82, v100, v101
	v_cvt_pk_bf16_f32 v83, v102, v103
	s_nop 1
	ds_read2_b64 v[96:99], v89 offset0:140 offset1:142
	ds_read2_b64 v[100:103], v88 offset0:204 offset1:206
	v_mov_b32_e32 v248, v252
	v_mov_b32_e32 v249, v251
	s_waitcnt lgkmcnt(7)
	v_mfma_f32_32x32x16_bf16 v[64:79], v[112:115], v[80:83], v[64:79]
	s_waitcnt lgkmcnt(6)
	v_mfma_f32_32x32x16_bf16 v[48:63], v[116:119], v[80:83], v[48:63]
	v_cvt_pk_bf16_f32 v80, v104, v105
	v_cvt_pk_bf16_f32 v81, v106, v107
	v_cvt_pk_bf16_f32 v82, v108, v109
	v_cvt_pk_bf16_f32 v83, v110, v111
	s_nop 1
	s_waitcnt lgkmcnt(5)
	v_mfma_f32_32x32x16_bf16 v[64:79], v[120:123], v[80:83], v[64:79]
	s_waitcnt lgkmcnt(4)
	v_mfma_f32_32x32x16_bf16 v[48:63], v[124:127], v[80:83], v[48:63]
	v_cvt_pk_bf16_f32 v80, v128, v129
	v_cvt_pk_bf16_f32 v81, v130, v131
	v_cvt_pk_bf16_f32 v82, v132, v133
	v_cvt_pk_bf16_f32 v83, v134, v135
	s_nop 1
	s_waitcnt lgkmcnt(3)
	v_mfma_f32_32x32x16_bf16 v[64:79], v[84:87], v[80:83], v[64:79]
	s_waitcnt lgkmcnt(2)
	v_mfma_f32_32x32x16_bf16 v[48:63], v[92:95], v[80:83], v[48:63]
	v_cvt_pk_bf16_f32 v80, v136, v137
	v_cvt_pk_bf16_f32 v81, v138, v139
	v_cvt_pk_bf16_f32 v82, v140, v141
	v_cvt_pk_bf16_f32 v83, v142, v143
	s_nop 1
	s_waitcnt lgkmcnt(1)
	v_mfma_f32_32x32x16_bf16 v[64:79], v[96:99], v[80:83], v[64:79]
	s_waitcnt lgkmcnt(0)
	v_mfma_f32_32x32x16_bf16 v[48:63], v[100:103], v[80:83], v[48:63]

; #define MFMA32(a, b, c) __builtin_amdgcn_mfma_f32_32x32x16_bf16((a), (b), (c), 0, 0, 0)
; DI void qk_tile(const u16* Ks, const bf16x8* qf, f32x16* s, int rl, int hh) {
; #pragma unroll
;   for (int kb = 0; kb < 2; ++kb) {
; #pragma unroll
;     for (int i = 0; i < 16; ++i) s[kb][i] = 0.f;
; #pragma unroll
;     for (int ks = 0; ks < 4; ++ks) {
;       bf16x8 a = *(const bf16x8*)(Ks + (kb * 32 + rl) * KVS + ks * 16 + hh * 8);
;       s[kb] = MFMA32(a, qf[ks], s[kb]);
;     }
;   }
; }
; DI void online_softmax(f32x16* s, uint32_t vm, float& m, float& l, f32x16* o) {
;   const unsigned long long ball = __ballot(vm == 0xffffffffu), bnone = __ballot(vm == 0u);
;   if (ball == ~0ull) osm<0>(s, vm, m, l, o);
;   else if ((ball | bnone) == ~0ull) osm<1>(s, vm, m, l, o);
;   else osm<2>(s, vm, m, l, o);
; }
.LBB0_1701:
	s_or_b64 exec, exec, s[12:13]
	v_cmp_ne_u32_e64 s[10:11], 0, v96
	s_mov_b64 vcc, s[10:11]
	s_cbranch_vccz .LBB0_1711
	s_mul_i32 s3, s29, 0x4800
	v_or_b32_e32 v250, s3, v0
	v_lshl_add_u32 v97, v246, 1, v250
	ds_read_b128 v[98:101], v97 offset:18432
	ds_read_b128 v[102:105], v97 offset:18464
	ds_read_b128 v[106:109], v97 offset:18496
	ds_read_b128 v[128:131], v97 offset:18528
	ds_read_b128 v[80:83], v97 offset:23040
	ds_read_b128 v[132:135], v97 offset:23072
	ds_read_b128 v[136:139], v97 offset:23104
	ds_read_b128 v[140:143], v97 offset:23136
	v_cmp_eq_u32_e32 vcc, -1, v96
	v_cmp_eq_u32_e64 s[12:13], 0, v96
	s_cmp_eq_u64 vcc, -1
	s_waitcnt lgkmcnt(7)
	v_mfma_f32_32x32x16_bf16 v[112:127], v[98:101], v[2:5], 0
	s_waitcnt lgkmcnt(6)
	v_mfma_f32_32x32x16_bf16 v[112:127], v[102:105], v[176:179], v[112:127]
	s_waitcnt lgkmcnt(5)
	v_mfma_f32_32x32x16_bf16 v[112:127], v[106:109], v[180:183], v[112:127]
	s_waitcnt lgkmcnt(4)
	v_mfma_f32_32x32x16_bf16 v[112:127], v[128:131], v[184:187], v[112:127]
	s_waitcnt lgkmcnt(3)
	v_mfma_f32_32x32x16_bf16 v[80:95], v[80:83], v[2:5], 0
	s_waitcnt lgkmcnt(2)
	v_mfma_f32_32x32x16_bf16 v[80:95], v[132:135], v[176:179], v[80:95]
	s_waitcnt lgkmcnt(1)
	v_mfma_f32_32x32x16_bf16 v[80:95], v[136:139], v[180:183], v[80:95]
	s_waitcnt lgkmcnt(0)
	v_mfma_f32_32x32x16_bf16 v[80:95], v[140:143], v[184:187], v[80:95]
	s_cbranch_scc1 .LBB0_1759
	s_or_b64 s[4:5], s[12:13], vcc
	s_cmp_lg_u64 s[4:5], -1
	s_cbranch_scc0 .LBB0_1763
	v_and_b32_e32 v97, 1, v96
	v_cmp_eq_u32_e32 vcc, 1, v97
	v_and_b32_e32 v98, 2, v96
	v_and_b32_e32 v100, 4, v96
	v_cndmask_b32_e32 v97, v204, v112, vcc
	v_cmp_ne_u32_e32 vcc, 0, v98
	v_and_b32_e32 v101, 8, v96
	v_and_b32_e32 v102, 16, v96
	v_cndmask_b32_e32 v98, v204, v113, vcc
	v_cmp_ne_u32_e32 vcc, 0, v100
	v_and_b32_e32 v103, 32, v96
	v_and_b32_e32 v104, 64, v96
	v_cndmask_b32_e32 v100, v204, v114, vcc
	v_cmp_ne_u32_e32 vcc, 0, v101
	v_and_b32_e32 v105, 0x80, v96
	v_and_b32_e32 v106, 0x100, v96
	v_cndmask_b32_e32 v101, v204, v115, vcc
	v_cmp_ne_u32_e32 vcc, 0, v102
	v_and_b32_e32 v107, 0x200, v96
	v_and_b32_e32 v108, 0x400, v96
	v_cndmask_b32_e32 v102, v204, v116, vcc
	v_cmp_ne_u32_e32 vcc, 0, v103
	v_and_b32_e32 v109, 0x800, v96
	v_and_b32_e32 v110, 0x1000, v96
	v_cndmask_b32_e32 v103, v204, v117, vcc
	v_cmp_ne_u32_e32 vcc, 0, v104
	v_and_b32_e32 v111, 0x2000, v96
	v_and_b32_e32 v128, 0x4000, v96
	v_cndmask_b32_e32 v104, v204, v118, vcc
	v_cmp_ne_u32_e32 vcc, 0, v105
	v_and_b32_e32 v129, 0x8000, v96
	v_and_b32_e32 v130, 0x10000, v96
	v_cndmask_b32_e32 v105, v204, v119, vcc
	v_cmp_ne_u32_e32 vcc, 0, v106
	v_and_b32_e32 v131, 0x20000, v96
	v_and_b32_e32 v132, 0x40000, v96
	v_cndmask_b32_e32 v106, v204, v120, vcc
	v_cmp_ne_u32_e32 vcc, 0, v107
	v_max3_f32 v99, v97, s77, v98
	v_and_b32_e32 v133, 0x80000, v96
	v_cndmask_b32_e32 v107, v204, v121, vcc
	v_cmp_ne_u32_e32 vcc, 0, v108
	v_max3_f32 v99, v99, v100, v101
	v_and_b32_e32 v134, 0x100000, v96
	v_cndmask_b32_e32 v108, v204, v122, vcc
	v_cmp_ne_u32_e32 vcc, 0, v109
	v_max3_f32 v99, v99, v102, v103
	v_and_b32_e32 v135, 0x200000, v96
	v_cndmask_b32_e32 v109, v204, v123, vcc
	v_cmp_ne_u32_e32 vcc, 0, v110
	v_max3_f32 v99, v99, v104, v105
	v_and_b32_e32 v136, 0x400000, v96
	v_cndmask_b32_e32 v110, v204, v124, vcc
	v_cmp_ne_u32_e32 vcc, 0, v111
	v_max3_f32 v99, v99, v106, v107
	v_and_b32_e32 v137, 0x800000, v96
	v_cndmask_b32_e32 v111, v204, v125, vcc
	v_cmp_ne_u32_e32 vcc, 0, v128
	v_max3_f32 v99, v99, v108, v109
	v_and_b32_e32 v138, 0x1000000, v96
	v_cndmask_b32_e32 v128, v204, v126, vcc
	v_cmp_ne_u32_e32 vcc, 0, v129
	v_max3_f32 v99, v99, v110, v111
	v_and_b32_e32 v139, 0x2000000, v96
	v_cndmask_b32_e32 v129, v204, v127, vcc
	v_cmp_ne_u32_e32 vcc, 0, v130
	v_max3_f32 v99, v99, v128, v129
	v_and_b32_e32 v140, 0x4000000, v96
	v_cndmask_b32_e32 v130, v204, v80, vcc
	v_cmp_ne_u32_e32 vcc, 0, v131
	v_and_b32_e32 v141, 0x8000000, v96
	v_and_b32_e32 v142, 0x10000000, v96
	v_cndmask_b32_e32 v131, v204, v81, vcc
	v_cmp_ne_u32_e32 vcc, 0, v132
	v_max3_f32 v99, v99, v130, v131
	v_and_b32_e32 v143, 0x20000000, v96
	v_cndmask_b32_e32 v132, v204, v82, vcc
	v_cmp_ne_u32_e32 vcc, 0, v133
	v_and_b32_e32 v202, 2.0, v96
	s_nop 0
	v_cndmask_b32_e32 v133, v204, v83, vcc
	v_cmp_ne_u32_e32 vcc, 0, v134
	v_max3_f32 v99, v99, v132, v133
	s_nop 0
	v_cndmask_b32_e32 v134, v204, v84, vcc
	v_cmp_ne_u32_e32 vcc, 0, v135
	s_nop 1
	v_cndmask_b32_e32 v135, v204, v85, vcc
	v_cmp_ne_u32_e32 vcc, 0, v136
	v_max3_f32 v99, v99, v134, v135
	s_nop 0
	v_cndmask_b32_e32 v136, v204, v86, vcc
	v_cmp_ne_u32_e32 vcc, 0, v137
; DI float fexp2(float x) { return __builtin_amdgcn_exp2f(x); }
; template <int MODE>
; DI void osm(f32x16* s, uint32_t vm, float& m, float& l, f32x16* o) {
;   float mx = -1e30f;
; #pragma unroll
;   for (int kb = 0; kb < 2; ++kb)
; #pragma unroll
;     for (int i = 0; i < 16; ++i) {
;       if (MODE == 2) s[kb][i] = ((vm >> (kb * 16 + i)) & 1u) ? s[kb][i] : -1e30f;
;       mx = fmaxf(mx, s[kb][i]);
;     }
;   mx *= SCL2;
;   if (MODE == 1) mx = vm ? mx : -1e30f;
;   mx = xmax32(mx);
;   const float mn = fmaxf(m, mx);
;   const float alpha = fexp2(m - mn);
;   const bool rowok = (MODE == 1) ? (vm != 0u) : true;
;   const float mu = (rowok && mn > -1e29f) ? mn : 1e30f;
;   float rs = 0.f;
; #pragma unroll
;   for (int kb = 0; kb < 2; ++kb)
; #pragma unroll
;     for (int i = 0; i < 16; ++i) {
;       const float pv = fexp2(__builtin_fmaf(s[kb][i], SCL2, -mu));
;       s[kb][i] = pv;
;       rs += pv;
;     }
;   rs = xsum32(rs);
;   l = l * alpha + rs;
;   if (__ballot(mn > m) != 0ull) {
; #pragma unroll
;     for (int db = 0; db < 2; ++db)
; #pragma unroll
;       for (int i = 0; i < 16; ++i) o[db][i] *= alpha;
;   }
;   m = mn;
; }
	s_nop 1
	v_cndmask_b32_e32 v137, v204, v87, vcc
	v_cmp_ne_u32_e32 vcc, 0, v138
	v_max3_f32 v99, v99, v136, v137
	s_nop 0
	v_cndmask_b32_e32 v138, v204, v88, vcc
	v_cmp_ne_u32_e32 vcc, 0, v139
	s_nop 1
	v_cndmask_b32_e32 v139, v204, v89, vcc
	v_cmp_ne_u32_e32 vcc, 0, v140
	v_max3_f32 v99, v99, v138, v139
	s_nop 0
	v_cndmask_b32_e32 v140, v204, v90, vcc
	v_cmp_ne_u32_e32 vcc, 0, v141
	s_nop 1
	v_cndmask_b32_e32 v141, v204, v91, vcc
	v_cmp_ne_u32_e32 vcc, 0, v142
	v_max3_f32 v99, v99, v140, v141
	s_nop 0
	v_cndmask_b32_e32 v142, v204, v92, vcc
	v_cmp_ne_u32_e32 vcc, 0, v143
	s_nop 1
	v_cndmask_b32_e32 v143, v204, v93, vcc
	v_cmp_ne_u32_e32 vcc, 0, v202
	v_max3_f32 v99, v99, v142, v143
	s_nop 0
	v_cndmask_b32_e32 v202, v204, v94, vcc
	v_cmp_gt_i32_e32 vcc, 0, v96
	s_nop 1
	v_cndmask_b32_e32 v229, v204, v95, vcc
	v_max3_f32 v96, v99, v202, v229
	v_mul_f32_e32 v96, 0x3e38aa3b, v96
	v_mov_b32_e32 v99, v96
	s_nop 1
	v_permlane32_swap_b32_e32 v96, v99
	v_max3_f32 v251, v249, v96, v99
	v_cmp_lt_f32_e32 vcc, s1, v251
	v_sub_f32_e32 v252, v249, v251
	s_nop 0
	v_cndmask_b32_e64 v253, v204, -v251, vcc
	v_fmamk_f32 v96, v97, 0x3e38aa3b, v253
	v_exp_f32_e32 v96, v96
	v_fmamk_f32 v97, v98, 0x3e38aa3b, v253
	v_exp_f32_e32 v97, v97
	v_fmamk_f32 v98, v100, 0x3e38aa3b, v253
	v_exp_f32_e32 v98, v98
	v_fmamk_f32 v99, v101, 0x3e38aa3b, v253
	v_exp_f32_e32 v99, v99
	v_add_f32_e32 v100, 0, v96
	v_add_f32_e32 v100, v97, v100
	v_add_f32_e32 v100, v98, v100
	v_add_f32_e32 v254, v99, v100
	v_fmamk_f32 v100, v102, 0x3e38aa3b, v253
	v_exp_f32_e32 v100, v100
	v_fmamk_f32 v101, v103, 0x3e38aa3b, v253
	v_exp_f32_e32 v101, v101
	v_fmamk_f32 v102, v104, 0x3e38aa3b, v253
	v_exp_f32_e32 v102, v102
	v_fmamk_f32 v103, v105, 0x3e38aa3b, v253
	v_exp_f32_e32 v103, v103
	v_add_f32_e32 v104, v100, v254
	v_add_f32_e32 v104, v101, v104
	v_add_f32_e32 v104, v102, v104
	v_add_f32_e32 v254, v103, v104
	v_fmamk_f32 v104, v106, 0x3e38aa3b, v253
	v_exp_f32_e32 v104, v104
	v_fmamk_f32 v105, v107, 0x3e38aa3b, v253
	v_exp_f32_e32 v105, v105
	v_fmamk_f32 v106, v108, 0x3e38aa3b, v253
	v_exp_f32_e32 v106, v106
	v_fmamk_f32 v107, v109, 0x3e38aa3b, v253
	v_exp_f32_e32 v107, v107
	v_add_f32_e32 v108, v104, v254
	v_add_f32_e32 v108, v105, v108
	v_add_f32_e32 v108, v106, v108
	v_add_f32_e32 v254, v107, v108
	v_fmamk_f32 v108, v110, 0x3e38aa3b, v253
	v_exp_f32_e32 v108, v108
	v_fmamk_f32 v109, v111, 0x3e38aa3b, v253
	v_exp_f32_e32 v109, v109
	v_fmamk_f32 v110, v128, 0x3e38aa3b, v253
	v_exp_f32_e32 v110, v110
	v_fmamk_f32 v111, v129, 0x3e38aa3b, v253
	v_exp_f32_e32 v111, v111
	v_add_f32_e32 v128, v108, v254
	v_add_f32_e32 v128, v109, v128
	v_add_f32_e32 v128, v110, v128
	v_add_f32_e32 v254, v111, v128
	v_fmamk_f32 v128, v130, 0x3e38aa3b, v253
	v_exp_f32_e32 v128, v128
	v_fmamk_f32 v129, v131, 0x3e38aa3b, v253
	v_exp_f32_e32 v129, v129
	v_fmamk_f32 v130, v132, 0x3e38aa3b, v253
	v_exp_f32_e32 v130, v130
	v_fmamk_f32 v131, v133, 0x3e38aa3b, v253
	v_exp_f32_e32 v131, v131
	v_add_f32_e32 v132, v128, v254
	v_add_f32_e32 v132, v129, v132
	v_add_f32_e32 v132, v130, v132
	v_add_f32_e32 v254, v131, v132
	v_fmamk_f32 v132, v134, 0x3e38aa3b, v253
	v_exp_f32_e32 v132, v132
	v_fmamk_f32 v133, v135, 0x3e38aa3b, v253
	v_exp_f32_e32 v133, v133
	v_fmamk_f32 v134, v136, 0x3e38aa3b, v253
	v_exp_f32_e32 v134, v134
	v_fmamk_f32 v135, v137, 0x3e38aa3b, v253
	v_exp_f32_e32 v135, v135
	v_add_f32_e32 v136, v132, v254
	v_add_f32_e32 v136, v133, v136
	v_add_f32_e32 v136, v134, v136
	v_add_f32_e32 v254, v135, v136
	v_fmamk_f32 v136, v138, 0x3e38aa3b, v253
	v_exp_f32_e32 v136, v136
	v_fmamk_f32 v137, v139, 0x3e38aa3b, v253
	v_exp_f32_e32 v137, v137
	v_fmamk_f32 v138, v140, 0x3e38aa3b, v253
	v_exp_f32_e32 v138, v138
	v_fmamk_f32 v139, v141, 0x3e38aa3b, v253
	v_exp_f32_e32 v139, v139
	v_add_f32_e32 v140, v136, v254
	v_add_f32_e32 v140, v137, v140
	v_add_f32_e32 v140, v138, v140
	v_add_f32_e32 v254, v139, v140
	v_fmamk_f32 v140, v142, 0x3e38aa3b, v253
	v_exp_f32_e32 v140, v140
	v_fmamk_f32 v141, v143, 0x3e38aa3b, v253
	v_exp_f32_e32 v141, v141
	v_fmamk_f32 v142, v202, 0x3e38aa3b, v253
	v_exp_f32_e32 v142, v142
	v_fmac_f32_e32 v253, 0x3e38aa3b, v229
	v_exp_f32_e32 v143, v253
	v_add_f32_e32 v202, v140, v254
	v_add_f32_e32 v202, v141, v202
	v_add_f32_e32 v202, v142, v202
	v_add_f32_e32 v229, v143, v202
	v_exp_f32_e32 v202, v252
	v_mov_b32_e32 v252, v229
	s_nop 1
	v_permlane32_swap_b32_e32 v229, v252
	v_cmp_gt_f32_e32 vcc, v251, v249
	v_add_f32_e32 v252, v229, v252
	s_cmp_lg_u64 vcc, 0
	v_fmac_f32_e32 v252, v248, v202
	s_cselect_b64 s[12:13], -1, 0
	s_cbranch_execnz .LBB0_1706

; #define MFMA32(a, b, c) __builtin_amdgcn_mfma_f32_32x32x16_bf16((a), (b), (c), 0, 0, 0)
; DI void pv_tile(const u16* Vs, const f32x16* s, f32x16* o, int rl, int hh) {
; #pragma unroll
;   for (int kk = 0; kk < 4; ++kk) {
;     const int kb = kk >> 1, i0 = 8 * (kk & 1);
;     bf16x8 pf = pack8(s[kb][i0], s[kb][i0 + 1], s[kb][i0 + 2], s[kb][i0 + 3], s[kb][i0 + 4], s[kb][i0 + 5], s[kb][i0 + 6], s[kb][i0 + 7]);
; #pragma unroll
;     for (int db = 0; db < 2; ++db) {
;       const u16* vp = Vs + (db * 32 + rl) * KVS + kk * 16 + hh * 4;
;       s16x4 lo = *(const s16x4*)vp, hi = *(const s16x4*)(vp + 8);
;       bf16x8 a = __builtin_shufflevector(lo, hi, 0, 1, 2, 3, 4, 5, 6, 7);
;       o[db] = MFMA32(a, pf, o[db]);
;     }
;   }
; }
.LBB0_1710:
	s_nop 0
	v_lshlrev_b32_e32 v84, 1, v246
	v_add3_u32 v88, v250, v247, v84
	s_nop 2
	v_add_u32_e32 v89, 0x6800, v88
	v_add_u32_e32 v88, 0x7800, v88
	ds_read2_b64 v[112:115], v89 offset0:128 offset1:130
	ds_read2_b64 v[116:119], v88 offset0:192 offset1:194
	ds_read2_b64 v[120:123], v89 offset0:132 offset1:134
	ds_read2_b64 v[124:127], v88 offset0:196 offset1:198
	ds_read2_b64 v[84:87], v89 offset0:136 offset1:138
	ds_read2_b64 v[92:95], v88 offset0:200 offset1:202
	v_cvt_pk_bf16_f32 v80, v96, v97
	v_cvt_pk_bf16_f32 v81, v98, v99
	v_cvt_pk_bf16_f32 v82, v100, v101
	v_cvt_pk_bf16_f32 v83, v102, v103
	s_nop 1
	ds_read2_b64 v[96:99], v89 offset0:140 offset1:142
	ds_read2_b64 v[100:103], v88 offset0:204 offset1:206
	v_mov_b32_e32 v248, v252
	v_mov_b32_e32 v249, v251
	s_waitcnt lgkmcnt(7)
	v_mfma_f32_32x32x16_bf16 v[64:79], v[112:115], v[80:83], v[64:79]
	s_waitcnt lgkmcnt(6)
	v_mfma_f32_32x32x16_bf16 v[48:63], v[116:119], v[80:83], v[48:63]
	v_cvt_pk_bf16_f32 v80, v104, v105
	v_cvt_pk_bf16_f32 v81, v106, v107
	v_cvt_pk_bf16_f32 v82, v108, v109
	v_cvt_pk_bf16_f32 v83, v110, v111
	s_nop 1
	s_waitcnt lgkmcnt(5)
	v_mfma_f32_32x32x16_bf16 v[64:79], v[120:123], v[80:83], v[64:79]
	s_waitcnt lgkmcnt(4)
	v_mfma_f32_32x32x16_bf16 v[48:63], v[124:127], v[80:83], v[48:63]
	v_cvt_pk_bf16_f32 v80, v128, v129
	v_cvt_pk_bf16_f32 v81, v130, v131
	v_cvt_pk_bf16_f32 v82, v132, v133
	v_cvt_pk_bf16_f32 v83, v134, v135
	s_nop 1
	s_waitcnt lgkmcnt(3)
	v_mfma_f32_32x32x16_bf16 v[64:79], v[84:87], v[80:83], v[64:79]
	s_waitcnt lgkmcnt(2)
	v_mfma_f32_32x32x16_bf16 v[48:63], v[92:95], v[80:83], v[48:63]
	v_cvt_pk_bf16_f32 v80, v136, v137
	v_cvt_pk_bf16_f32 v81, v138, v139
	v_cvt_pk_bf16_f32 v82, v140, v141
	v_cvt_pk_bf16_f32 v83, v142, v143
	s_nop 1
	s_waitcnt lgkmcnt(1)
	v_mfma_f32_32x32x16_bf16 v[64:79], v[96:99], v[80:83], v[64:79]
	s_waitcnt lgkmcnt(0)
	v_mfma_f32_32x32x16_bf16 v[48:63], v[100:103], v[80:83], v[48:63]

; #define MFMA32(a, b, c) __builtin_amdgcn_mfma_f32_32x32x16_bf16((a), (b), (c), 0, 0, 0)
; DI void qk_tile(const u16* Ks, const bf16x8* qf, f32x16* s, int rl, int hh) {
; #pragma unroll
;   for (int kb = 0; kb < 2; ++kb) {
; #pragma unroll
;     for (int i = 0; i < 16; ++i) s[kb][i] = 0.f;
; #pragma unroll
;     for (int ks = 0; ks < 4; ++ks) {
;       bf16x8 a = *(const bf16x8*)(Ks + (kb * 32 + rl) * KVS + ks * 16 + hh * 8);
;       s[kb] = MFMA32(a, qf[ks], s[kb]);
;     }
;   }
; }
; DI void online_softmax(f32x16* s, uint32_t vm, float& m, float& l, f32x16* o) {
;   const unsigned long long ball = __ballot(vm == 0xffffffffu), bnone = __ballot(vm == 0u);
;   if (ball == ~0ull) osm<0>(s, vm, m, l, o);
;   else if ((ball | bnone) == ~0ull) osm<1>(s, vm, m, l, o);
;   else osm<2>(s, vm, m, l, o);
; }
.LBB0_1718:
	s_or_b64 exec, exec, s[12:13]
	v_cmp_ne_u32_e64 s[10:11], 0, v96
	s_mov_b64 vcc, s[10:11]
	s_cbranch_vccz .LBB0_1728
	s_mul_i32 s3, s29, 0x4800
	v_or_b32_e32 v250, s3, v0
	v_lshl_add_u32 v97, v246, 1, v250
	ds_read_b128 v[98:101], v97 offset:36864
	ds_read_b128 v[102:105], v97 offset:36896
	ds_read_b128 v[106:109], v97 offset:36928
	ds_read_b128 v[128:131], v97 offset:36960
	ds_read_b128 v[80:83], v97 offset:41472
	ds_read_b128 v[132:135], v97 offset:41504
	ds_read_b128 v[136:139], v97 offset:41536
	ds_read_b128 v[140:143], v97 offset:41568
	v_cmp_eq_u32_e32 vcc, -1, v96
	v_cmp_eq_u32_e64 s[12:13], 0, v96
	s_cmp_eq_u64 vcc, -1
	s_waitcnt lgkmcnt(7)
	v_mfma_f32_32x32x16_bf16 v[112:127], v[98:101], v[2:5], 0
	s_waitcnt lgkmcnt(6)
	v_mfma_f32_32x32x16_bf16 v[112:127], v[102:105], v[176:179], v[112:127]
	s_waitcnt lgkmcnt(5)
	v_mfma_f32_32x32x16_bf16 v[112:127], v[106:109], v[180:183], v[112:127]
	s_waitcnt lgkmcnt(4)
	v_mfma_f32_32x32x16_bf16 v[112:127], v[128:131], v[184:187], v[112:127]
	s_waitcnt lgkmcnt(3)
	v_mfma_f32_32x32x16_bf16 v[80:95], v[80:83], v[2:5], 0
	s_waitcnt lgkmcnt(2)
	v_mfma_f32_32x32x16_bf16 v[80:95], v[132:135], v[176:179], v[80:95]
	s_waitcnt lgkmcnt(1)
	v_mfma_f32_32x32x16_bf16 v[80:95], v[136:139], v[180:183], v[80:95]
	s_waitcnt lgkmcnt(0)
	v_mfma_f32_32x32x16_bf16 v[80:95], v[140:143], v[184:187], v[80:95]
	s_cbranch_scc1 .LBB0_1760
	s_or_b64 s[4:5], s[12:13], vcc
	s_cmp_lg_u64 s[4:5], -1
	s_cbranch_scc0 .LBB0_1764
	v_and_b32_e32 v97, 1, v96
	v_cmp_eq_u32_e32 vcc, 1, v97
	v_and_b32_e32 v98, 2, v96
	v_and_b32_e32 v100, 4, v96
	v_cndmask_b32_e32 v97, v204, v112, vcc
	v_cmp_ne_u32_e32 vcc, 0, v98
	v_and_b32_e32 v101, 8, v96
	v_and_b32_e32 v102, 16, v96
	v_cndmask_b32_e32 v98, v204, v113, vcc
	v_cmp_ne_u32_e32 vcc, 0, v100
	v_and_b32_e32 v103, 32, v96
	v_and_b32_e32 v104, 64, v96
	v_cndmask_b32_e32 v100, v204, v114, vcc
	v_cmp_ne_u32_e32 vcc, 0, v101
	v_and_b32_e32 v105, 0x80, v96
	v_and_b32_e32 v106, 0x100, v96
	v_cndmask_b32_e32 v101, v204, v115, vcc
	v_cmp_ne_u32_e32 vcc, 0, v102
	v_and_b32_e32 v107, 0x200, v96
	v_and_b32_e32 v108, 0x400, v96
	v_cndmask_b32_e32 v102, v204, v116, vcc
	v_cmp_ne_u32_e32 vcc, 0, v103
	v_and_b32_e32 v109, 0x800, v96
	v_and_b32_e32 v110, 0x1000, v96
	v_cndmask_b32_e32 v103, v204, v117, vcc
	v_cmp_ne_u32_e32 vcc, 0, v104
	v_and_b32_e32 v111, 0x2000, v96
	v_and_b32_e32 v128, 0x4000, v96
	v_cndmask_b32_e32 v104, v204, v118, vcc
	v_cmp_ne_u32_e32 vcc, 0, v105
	v_and_b32_e32 v129, 0x8000, v96
	v_and_b32_e32 v130, 0x10000, v96
	v_cndmask_b32_e32 v105, v204, v119, vcc
	v_cmp_ne_u32_e32 vcc, 0, v106
	v_and_b32_e32 v131, 0x20000, v96
	v_and_b32_e32 v132, 0x40000, v96
	v_cndmask_b32_e32 v106, v204, v120, vcc
	v_cmp_ne_u32_e32 vcc, 0, v107
	v_max3_f32 v99, v97, s77, v98
	v_and_b32_e32 v133, 0x80000, v96
	v_cndmask_b32_e32 v107, v204, v121, vcc
	v_cmp_ne_u32_e32 vcc, 0, v108
	v_max3_f32 v99, v99, v100, v101
	v_and_b32_e32 v134, 0x100000, v96
	v_cndmask_b32_e32 v108, v204, v122, vcc
	v_cmp_ne_u32_e32 vcc, 0, v109
	v_max3_f32 v99, v99, v102, v103
	v_and_b32_e32 v135, 0x200000, v96
	v_cndmask_b32_e32 v109, v204, v123, vcc
	v_cmp_ne_u32_e32 vcc, 0, v110
	v_max3_f32 v99, v99, v104, v105
	v_and_b32_e32 v136, 0x400000, v96
	v_cndmask_b32_e32 v110, v204, v124, vcc
	v_cmp_ne_u32_e32 vcc, 0, v111
	v_max3_f32 v99, v99, v106, v107
	v_and_b32_e32 v137, 0x800000, v96
	v_cndmask_b32_e32 v111, v204, v125, vcc
	v_cmp_ne_u32_e32 vcc, 0, v128
	v_max3_f32 v99, v99, v108, v109
	v_and_b32_e32 v138, 0x1000000, v96
	v_cndmask_b32_e32 v128, v204, v126, vcc
	v_cmp_ne_u32_e32 vcc, 0, v129
	v_max3_f32 v99, v99, v110, v111
	v_and_b32_e32 v139, 0x2000000, v96
	v_cndmask_b32_e32 v129, v204, v127, vcc
	v_cmp_ne_u32_e32 vcc, 0, v130
	v_max3_f32 v99, v99, v128, v129
	v_and_b32_e32 v140, 0x4000000, v96
	v_cndmask_b32_e32 v130, v204, v80, vcc
	v_cmp_ne_u32_e32 vcc, 0, v131
	v_and_b32_e32 v141, 0x8000000, v96
	v_and_b32_e32 v142, 0x10000000, v96
	v_cndmask_b32_e32 v131, v204, v81, vcc
	v_cmp_ne_u32_e32 vcc, 0, v132
	v_max3_f32 v99, v99, v130, v131
	v_and_b32_e32 v143, 0x20000000, v96
	v_cndmask_b32_e32 v132, v204, v82, vcc
	v_cmp_ne_u32_e32 vcc, 0, v133
	v_and_b32_e32 v202, 2.0, v96
	s_nop 0
	v_cndmask_b32_e32 v133, v204, v83, vcc
	v_cmp_ne_u32_e32 vcc, 0, v134
	v_max3_f32 v99, v99, v132, v133
	s_nop 0
	v_cndmask_b32_e32 v134, v204, v84, vcc
	v_cmp_ne_u32_e32 vcc, 0, v135
	s_nop 1
	v_cndmask_b32_e32 v135, v204, v85, vcc
	v_cmp_ne_u32_e32 vcc, 0, v136
	v_max3_f32 v99, v99, v134, v135
	s_nop 0
	v_cndmask_b32_e32 v136, v204, v86, vcc
	v_cmp_ne_u32_e32 vcc, 0, v137
; DI float fexp2(float x) { return __builtin_amdgcn_exp2f(x); }
; template <int MODE>
; DI void osm(f32x16* s, uint32_t vm, float& m, float& l, f32x16* o) {
;   float mx = -1e30f;
; #pragma unroll
;   for (int kb = 0; kb < 2; ++kb)
; #pragma unroll
;     for (int i = 0; i < 16; ++i) {
;       if (MODE == 2) s[kb][i] = ((vm >> (kb * 16 + i)) & 1u) ? s[kb][i] : -1e30f;
;       mx = fmaxf(mx, s[kb][i]);
;     }
;   mx *= SCL2;
;   if (MODE == 1) mx = vm ? mx : -1e30f;
;   mx = xmax32(mx);
;   const float mn = fmaxf(m, mx);
;   const float alpha = fexp2(m - mn);
;   const bool rowok = (MODE == 1) ? (vm != 0u) : true;
;   const float mu = (rowok && mn > -1e29f) ? mn : 1e30f;
;   float rs = 0.f;
; #pragma unroll
;   for (int kb = 0; kb < 2; ++kb)
; #pragma unroll
;     for (int i = 0; i < 16; ++i) {
;       const float pv = fexp2(__builtin_fmaf(s[kb][i], SCL2, -mu));
;       s[kb][i] = pv;
;       rs += pv;
;     }
;   rs = xsum32(rs);
;   l = l * alpha + rs;
;   if (__ballot(mn > m) != 0ull) {
; #pragma unroll
;     for (int db = 0; db < 2; ++db)
; #pragma unroll
;       for (int i = 0; i < 16; ++i) o[db][i] *= alpha;
;   }
;   m = mn;
; }
	s_nop 1
	v_cndmask_b32_e32 v137, v204, v87, vcc
	v_cmp_ne_u32_e32 vcc, 0, v138
	v_max3_f32 v99, v99, v136, v137
	s_nop 0
	v_cndmask_b32_e32 v138, v204, v88, vcc
	v_cmp_ne_u32_e32 vcc, 0, v139
	s_nop 1
	v_cndmask_b32_e32 v139, v204, v89, vcc
	v_cmp_ne_u32_e32 vcc, 0, v140
	v_max3_f32 v99, v99, v138, v139
	s_nop 0
	v_cndmask_b32_e32 v140, v204, v90, vcc
	v_cmp_ne_u32_e32 vcc, 0, v141
	s_nop 1
	v_cndmask_b32_e32 v141, v204, v91, vcc
	v_cmp_ne_u32_e32 vcc, 0, v142
	v_max3_f32 v99, v99, v140, v141
	s_nop 0
	v_cndmask_b32_e32 v142, v204, v92, vcc
	v_cmp_ne_u32_e32 vcc, 0, v143
	s_nop 1
	v_cndmask_b32_e32 v143, v204, v93, vcc
	v_cmp_ne_u32_e32 vcc, 0, v202
	v_max3_f32 v99, v99, v142, v143
	s_nop 0
	v_cndmask_b32_e32 v202, v204, v94, vcc
	v_cmp_gt_i32_e32 vcc, 0, v96
	s_nop 1
	v_cndmask_b32_e32 v229, v204, v95, vcc
	v_max3_f32 v96, v99, v202, v229
	v_mul_f32_e32 v96, 0x3e38aa3b, v96
	v_mov_b32_e32 v99, v96
	s_nop 1
	v_permlane32_swap_b32_e32 v96, v99
	v_max3_f32 v251, v249, v96, v99
	v_cmp_lt_f32_e32 vcc, s1, v251
	v_sub_f32_e32 v252, v249, v251
	s_nop 0
	v_cndmask_b32_e64 v253, v204, -v251, vcc
	v_fmamk_f32 v96, v97, 0x3e38aa3b, v253
	v_exp_f32_e32 v96, v96
	v_fmamk_f32 v97, v98, 0x3e38aa3b, v253
	v_exp_f32_e32 v97, v97
	v_fmamk_f32 v98, v100, 0x3e38aa3b, v253
	v_exp_f32_e32 v98, v98
	v_fmamk_f32 v99, v101, 0x3e38aa3b, v253
	v_exp_f32_e32 v99, v99
	v_add_f32_e32 v100, 0, v96
	v_add_f32_e32 v100, v97, v100
	v_add_f32_e32 v100, v98, v100
	v_add_f32_e32 v254, v99, v100
	v_fmamk_f32 v100, v102, 0x3e38aa3b, v253
	v_exp_f32_e32 v100, v100
	v_fmamk_f32 v101, v103, 0x3e38aa3b, v253
	v_exp_f32_e32 v101, v101
	v_fmamk_f32 v102, v104, 0x3e38aa3b, v253
	v_exp_f32_e32 v102, v102
	v_fmamk_f32 v103, v105, 0x3e38aa3b, v253
	v_exp_f32_e32 v103, v103
	v_add_f32_e32 v104, v100, v254
	v_add_f32_e32 v104, v101, v104
	v_add_f32_e32 v104, v102, v104
	v_add_f32_e32 v254, v103, v104
	v_fmamk_f32 v104, v106, 0x3e38aa3b, v253
	v_exp_f32_e32 v104, v104
	v_fmamk_f32 v105, v107, 0x3e38aa3b, v253
	v_exp_f32_e32 v105, v105
	v_fmamk_f32 v106, v108, 0x3e38aa3b, v253
	v_exp_f32_e32 v106, v106
	v_fmamk_f32 v107, v109, 0x3e38aa3b, v253
	v_exp_f32_e32 v107, v107
	v_add_f32_e32 v108, v104, v254
	v_add_f32_e32 v108, v105, v108
	v_add_f32_e32 v108, v106, v108
	v_add_f32_e32 v254, v107, v108
	v_fmamk_f32 v108, v110, 0x3e38aa3b, v253
	v_exp_f32_e32 v108, v108
	v_fmamk_f32 v109, v111, 0x3e38aa3b, v253
	v_exp_f32_e32 v109, v109
	v_fmamk_f32 v110, v128, 0x3e38aa3b, v253
	v_exp_f32_e32 v110, v110
	v_fmamk_f32 v111, v129, 0x3e38aa3b, v253
	v_exp_f32_e32 v111, v111
	v_add_f32_e32 v128, v108, v254
	v_add_f32_e32 v128, v109, v128
	v_add_f32_e32 v128, v110, v128
	v_add_f32_e32 v254, v111, v128
	v_fmamk_f32 v128, v130, 0x3e38aa3b, v253
	v_exp_f32_e32 v128, v128
	v_fmamk_f32 v129, v131, 0x3e38aa3b, v253
	v_exp_f32_e32 v129, v129
	v_fmamk_f32 v130, v132, 0x3e38aa3b, v253
	v_exp_f32_e32 v130, v130
	v_fmamk_f32 v131, v133, 0x3e38aa3b, v253
	v_exp_f32_e32 v131, v131
	v_add_f32_e32 v132, v128, v254
	v_add_f32_e32 v132, v129, v132
	v_add_f32_e32 v132, v130, v132
	v_add_f32_e32 v254, v131, v132
	v_fmamk_f32 v132, v134, 0x3e38aa3b, v253
	v_exp_f32_e32 v132, v132
	v_fmamk_f32 v133, v135, 0x3e38aa3b, v253
	v_exp_f32_e32 v133, v133
	v_fmamk_f32 v134, v136, 0x3e38aa3b, v253
	v_exp_f32_e32 v134, v134
	v_fmamk_f32 v135, v137, 0x3e38aa3b, v253
	v_exp_f32_e32 v135, v135
	v_add_f32_e32 v136, v132, v254
	v_add_f32_e32 v136, v133, v136
	v_add_f32_e32 v136, v134, v136
	v_add_f32_e32 v254, v135, v136
	v_fmamk_f32 v136, v138, 0x3e38aa3b, v253
	v_exp_f32_e32 v136, v136
	v_fmamk_f32 v137, v139, 0x3e38aa3b, v253
	v_exp_f32_e32 v137, v137
	v_fmamk_f32 v138, v140, 0x3e38aa3b, v253
	v_exp_f32_e32 v138, v138
	v_fmamk_f32 v139, v141, 0x3e38aa3b, v253
	v_exp_f32_e32 v139, v139
	v_add_f32_e32 v140, v136, v254
	v_add_f32_e32 v140, v137, v140
	v_add_f32_e32 v140, v138, v140
	v_add_f32_e32 v254, v139, v140
	v_fmamk_f32 v140, v142, 0x3e38aa3b, v253
	v_exp_f32_e32 v140, v140
	v_fmamk_f32 v141, v143, 0x3e38aa3b, v253
	v_exp_f32_e32 v141, v141
	v_fmamk_f32 v142, v202, 0x3e38aa3b, v253
	v_exp_f32_e32 v142, v142
	v_fmac_f32_e32 v253, 0x3e38aa3b, v229
	v_exp_f32_e32 v143, v253
	v_add_f32_e32 v202, v140, v254
	v_add_f32_e32 v202, v141, v202
	v_add_f32_e32 v202, v142, v202
	v_add_f32_e32 v229, v143, v202
	v_exp_f32_e32 v202, v252
	v_mov_b32_e32 v252, v229
	s_nop 1
	v_permlane32_swap_b32_e32 v229, v252
	v_cmp_gt_f32_e32 vcc, v251, v249
	v_add_f32_e32 v252, v229, v252
	s_cmp_lg_u64 vcc, 0
	v_fmac_f32_e32 v252, v248, v202
	s_cselect_b64 s[12:13], -1, 0
	s_cbranch_execnz .LBB0_1723

; #define MFMA32(a, b, c) __builtin_amdgcn_mfma_f32_32x32x16_bf16((a), (b), (c), 0, 0, 0)
; DI void pv_tile(const u16* Vs, const f32x16* s, f32x16* o, int rl, int hh) {
; #pragma unroll
;   for (int kk = 0; kk < 4; ++kk) {
;     const int kb = kk >> 1, i0 = 8 * (kk & 1);
;     bf16x8 pf = pack8(s[kb][i0], s[kb][i0 + 1], s[kb][i0 + 2], s[kb][i0 + 3], s[kb][i0 + 4], s[kb][i0 + 5], s[kb][i0 + 6], s[kb][i0 + 7]);
; #pragma unroll
;     for (int db = 0; db < 2; ++db) {
;       const u16* vp = Vs + (db * 32 + rl) * KVS + kk * 16 + hh * 4;
;       s16x4 lo = *(const s16x4*)vp, hi = *(const s16x4*)(vp + 8);
;       bf16x8 a = __builtin_shufflevector(lo, hi, 0, 1, 2, 3, 4, 5, 6, 7);
;       o[db] = MFMA32(a, pf, o[db]);
;     }
;   }
; }
.LBB0_1727:
	s_nop 0
	v_lshlrev_b32_e32 v84, 1, v246
	v_add3_u32 v88, v250, v247, v84
	s_nop 2
	v_add_u32_e32 v89, 0xb000, v88
	v_add_u32_e32 v88, 0xc000, v88
	ds_read2_b64 v[112:115], v89 offset0:128 offset1:130
	ds_read2_b64 v[116:119], v88 offset0:192 offset1:194
	ds_read2_b64 v[120:123], v89 offset0:132 offset1:134
	ds_read2_b64 v[124:127], v88 offset0:196 offset1:198
	ds_read2_b64 v[84:87], v89 offset0:136 offset1:138
	ds_read2_b64 v[92:95], v88 offset0:200 offset1:202
	v_cvt_pk_bf16_f32 v80, v96, v97
	v_cvt_pk_bf16_f32 v81, v98, v99
	v_cvt_pk_bf16_f32 v82, v100, v101
	v_cvt_pk_bf16_f32 v83, v102, v103
	s_nop 1
	ds_read2_b64 v[96:99], v89 offset0:140 offset1:142
	ds_read2_b64 v[100:103], v88 offset0:204 offset1:206
	v_mov_b32_e32 v248, v252
	v_mov_b32_e32 v249, v251
	s_waitcnt lgkmcnt(7)
	v_mfma_f32_32x32x16_bf16 v[64:79], v[112:115], v[80:83], v[64:79]
	s_waitcnt lgkmcnt(6)
	v_mfma_f32_32x32x16_bf16 v[48:63], v[116:119], v[80:83], v[48:63]
	v_cvt_pk_bf16_f32 v80, v104, v105
	v_cvt_pk_bf16_f32 v81, v106, v107
	v_cvt_pk_bf16_f32 v82, v108, v109
	v_cvt_pk_bf16_f32 v83, v110, v111
	s_nop 1
	s_waitcnt lgkmcnt(5)
	v_mfma_f32_32x32x16_bf16 v[64:79], v[120:123], v[80:83], v[64:79]
	s_waitcnt lgkmcnt(4)
	v_mfma_f32_32x32x16_bf16 v[48:63], v[124:127], v[80:83], v[48:63]
	v_cvt_pk_bf16_f32 v80, v128, v129
	v_cvt_pk_bf16_f32 v81, v130, v131
	v_cvt_pk_bf16_f32 v82, v132, v133
	v_cvt_pk_bf16_f32 v83, v134, v135
	s_nop 1
	s_waitcnt lgkmcnt(3)
	v_mfma_f32_32x32x16_bf16 v[64:79], v[84:87], v[80:83], v[64:79]
	s_waitcnt lgkmcnt(2)
	v_mfma_f32_32x32x16_bf16 v[48:63], v[92:95], v[80:83], v[48:63]
	v_cvt_pk_bf16_f32 v80, v136, v137
	v_cvt_pk_bf16_f32 v81, v138, v139
	v_cvt_pk_bf16_f32 v82, v140, v141
	v_cvt_pk_bf16_f32 v83, v142, v143
	s_nop 1
	s_waitcnt lgkmcnt(1)
	v_mfma_f32_32x32x16_bf16 v[64:79], v[96:99], v[80:83], v[64:79]
	s_waitcnt lgkmcnt(0)
	v_mfma_f32_32x32x16_bf16 v[48:63], v[100:103], v[80:83], v[48:63]

; #define MFMA32(a, b, c) __builtin_amdgcn_mfma_f32_32x32x16_bf16((a), (b), (c), 0, 0, 0)
; DI void qk_tile(const u16* Ks, const bf16x8* qf, f32x16* s, int rl, int hh) {
; #pragma unroll
;   for (int kb = 0; kb < 2; ++kb) {
; #pragma unroll
;     for (int i = 0; i < 16; ++i) s[kb][i] = 0.f;
; #pragma unroll
;     for (int ks = 0; ks < 4; ++ks) {
;       bf16x8 a = *(const bf16x8*)(Ks + (kb * 32 + rl) * KVS + ks * 16 + hh * 8);
;       s[kb] = MFMA32(a, qf[ks], s[kb]);
;     }
;   }
; }
; DI void online_softmax(f32x16* s, uint32_t vm, float& m, float& l, f32x16* o) {
;   const unsigned long long ball = __ballot(vm == 0xffffffffu), bnone = __ballot(vm == 0u);
;   if (ball == ~0ull) osm<0>(s, vm, m, l, o);
;   else if ((ball | bnone) == ~0ull) osm<1>(s, vm, m, l, o);
;   else osm<2>(s, vm, m, l, o);
; }
.LBB0_1735:
	s_or_b64 exec, exec, s[12:13]
	v_cmp_ne_u32_e64 s[10:11], 0, v96
	s_mov_b64 vcc, s[10:11]
	s_cbranch_vccz .LBB0_1745
	s_mulk_i32 s29, 0x4800
	v_or_b32_e32 v250, s29, v0
	v_lshl_add_u32 v97, v246, 1, v250
	ds_read_b128 v[98:101], v97 offset:55296
	ds_read_b128 v[102:105], v97 offset:55328
	ds_read_b128 v[106:109], v97 offset:55360
	ds_read_b128 v[128:131], v97 offset:55392
	ds_read_b128 v[80:83], v97 offset:59904
	ds_read_b128 v[132:135], v97 offset:59936
	ds_read_b128 v[136:139], v97 offset:59968
	ds_read_b128 v[140:143], v97 offset:60000
	v_cmp_eq_u32_e32 vcc, -1, v96
	v_cmp_eq_u32_e64 s[12:13], 0, v96
	s_cmp_eq_u64 vcc, -1
	s_waitcnt lgkmcnt(7)
	v_mfma_f32_32x32x16_bf16 v[112:127], v[98:101], v[2:5], 0
	s_waitcnt lgkmcnt(6)
	v_mfma_f32_32x32x16_bf16 v[112:127], v[102:105], v[176:179], v[112:127]
	s_waitcnt lgkmcnt(5)
	v_mfma_f32_32x32x16_bf16 v[112:127], v[106:109], v[180:183], v[112:127]
	s_waitcnt lgkmcnt(4)
	v_mfma_f32_32x32x16_bf16 v[112:127], v[128:131], v[184:187], v[112:127]
	s_waitcnt lgkmcnt(3)
	v_mfma_f32_32x32x16_bf16 v[80:95], v[80:83], v[2:5], 0
	s_waitcnt lgkmcnt(2)
	v_mfma_f32_32x32x16_bf16 v[80:95], v[132:135], v[176:179], v[80:95]
	s_waitcnt lgkmcnt(1)
	v_mfma_f32_32x32x16_bf16 v[80:95], v[136:139], v[180:183], v[80:95]
	s_waitcnt lgkmcnt(0)
	v_mfma_f32_32x32x16_bf16 v[80:95], v[140:143], v[184:187], v[80:95]
	s_cbranch_scc1 .LBB0_1761
	s_or_b64 s[4:5], s[12:13], vcc
	s_cmp_lg_u64 s[4:5], -1
	s_cbranch_scc0 .LBB0_1765
	v_and_b32_e32 v97, 1, v96
	v_cmp_eq_u32_e32 vcc, 1, v97
	v_and_b32_e32 v98, 2, v96
	v_and_b32_e32 v100, 4, v96
	v_cndmask_b32_e32 v97, v204, v112, vcc
	v_cmp_ne_u32_e32 vcc, 0, v98
	v_and_b32_e32 v101, 8, v96
	v_and_b32_e32 v102, 16, v96
	v_cndmask_b32_e32 v98, v204, v113, vcc
	v_cmp_ne_u32_e32 vcc, 0, v100
	v_and_b32_e32 v103, 32, v96
	v_and_b32_e32 v104, 64, v96
	v_cndmask_b32_e32 v100, v204, v114, vcc
	v_cmp_ne_u32_e32 vcc, 0, v101
	v_and_b32_e32 v105, 0x80, v96
	v_and_b32_e32 v106, 0x100, v96
	v_cndmask_b32_e32 v101, v204, v115, vcc
	v_cmp_ne_u32_e32 vcc, 0, v102
	v_and_b32_e32 v107, 0x200, v96
	v_and_b32_e32 v108, 0x400, v96
	v_cndmask_b32_e32 v102, v204, v116, vcc
	v_cmp_ne_u32_e32 vcc, 0, v103
	v_and_b32_e32 v109, 0x800, v96
	v_and_b32_e32 v110, 0x1000, v96
	v_cndmask_b32_e32 v103, v204, v117, vcc
	v_cmp_ne_u32_e32 vcc, 0, v104
	v_and_b32_e32 v111, 0x2000, v96
	v_and_b32_e32 v128, 0x4000, v96
	v_cndmask_b32_e32 v104, v204, v118, vcc
	v_cmp_ne_u32_e32 vcc, 0, v105
	v_and_b32_e32 v129, 0x8000, v96
	v_and_b32_e32 v130, 0x10000, v96
	v_cndmask_b32_e32 v105, v204, v119, vcc
	v_cmp_ne_u32_e32 vcc, 0, v106
	v_and_b32_e32 v131, 0x20000, v96
	v_and_b32_e32 v132, 0x40000, v96
	v_cndmask_b32_e32 v106, v204, v120, vcc
	v_cmp_ne_u32_e32 vcc, 0, v107
	v_max3_f32 v99, v97, s77, v98
	v_and_b32_e32 v133, 0x80000, v96
	v_cndmask_b32_e32 v107, v204, v121, vcc
	v_cmp_ne_u32_e32 vcc, 0, v108
	v_max3_f32 v99, v99, v100, v101
	v_and_b32_e32 v134, 0x100000, v96
	v_cndmask_b32_e32 v108, v204, v122, vcc
	v_cmp_ne_u32_e32 vcc, 0, v109
	v_max3_f32 v99, v99, v102, v103
	v_and_b32_e32 v135, 0x200000, v96
	v_cndmask_b32_e32 v109, v204, v123, vcc
	v_cmp_ne_u32_e32 vcc, 0, v110
	v_max3_f32 v99, v99, v104, v105
	v_and_b32_e32 v136, 0x400000, v96
	v_cndmask_b32_e32 v110, v204, v124, vcc
	v_cmp_ne_u32_e32 vcc, 0, v111
	v_max3_f32 v99, v99, v106, v107
	v_and_b32_e32 v137, 0x800000, v96
	v_cndmask_b32_e32 v111, v204, v125, vcc
	v_cmp_ne_u32_e32 vcc, 0, v128
	v_max3_f32 v99, v99, v108, v109
	v_and_b32_e32 v138, 0x1000000, v96
	v_cndmask_b32_e32 v128, v204, v126, vcc
	v_cmp_ne_u32_e32 vcc, 0, v129
	v_max3_f32 v99, v99, v110, v111
	v_and_b32_e32 v139, 0x2000000, v96
	v_cndmask_b32_e32 v129, v204, v127, vcc
	v_cmp_ne_u32_e32 vcc, 0, v130
	v_max3_f32 v99, v99, v128, v129
	v_and_b32_e32 v140, 0x4000000, v96
	v_cndmask_b32_e32 v130, v204, v80, vcc
	v_cmp_ne_u32_e32 vcc, 0, v131
	v_and_b32_e32 v141, 0x8000000, v96
	v_and_b32_e32 v142, 0x10000000, v96
	v_cndmask_b32_e32 v131, v204, v81, vcc
	v_cmp_ne_u32_e32 vcc, 0, v132
	v_max3_f32 v99, v99, v130, v131
	v_and_b32_e32 v143, 0x20000000, v96
	v_cndmask_b32_e32 v132, v204, v82, vcc
	v_cmp_ne_u32_e32 vcc, 0, v133
	v_and_b32_e32 v202, 2.0, v96
	s_nop 0
	v_cndmask_b32_e32 v133, v204, v83, vcc
	v_cmp_ne_u32_e32 vcc, 0, v134
	v_max3_f32 v99, v99, v132, v133
	s_nop 0
	v_cndmask_b32_e32 v134, v204, v84, vcc
	v_cmp_ne_u32_e32 vcc, 0, v135
	s_nop 1
	v_cndmask_b32_e32 v135, v204, v85, vcc
	v_cmp_ne_u32_e32 vcc, 0, v136
	v_max3_f32 v99, v99, v134, v135
	s_nop 0
	v_cndmask_b32_e32 v136, v204, v86, vcc
	v_cmp_ne_u32_e32 vcc, 0, v137
; DI float fexp2(float x) { return __builtin_amdgcn_exp2f(x); }
; template <int MODE>
; DI void osm(f32x16* s, uint32_t vm, float& m, float& l, f32x16* o) {
;   float mx = -1e30f;
; #pragma unroll
;   for (int kb = 0; kb < 2; ++kb)
; #pragma unroll
;     for (int i = 0; i < 16; ++i) {
;       if (MODE == 2) s[kb][i] = ((vm >> (kb * 16 + i)) & 1u) ? s[kb][i] : -1e30f;
;       mx = fmaxf(mx, s[kb][i]);
;     }
;   mx *= SCL2;
;   if (MODE == 1) mx = vm ? mx : -1e30f;
;   mx = xmax32(mx);
;   const float mn = fmaxf(m, mx);
;   const float alpha = fexp2(m - mn);
;   const bool rowok = (MODE == 1) ? (vm != 0u) : true;
;   const float mu = (rowok && mn > -1e29f) ? mn : 1e30f;
;   float rs = 0.f;
; #pragma unroll
;   for (int kb = 0; kb < 2; ++kb)
; #pragma unroll
;     for (int i = 0; i < 16; ++i) {
;       const float pv = fexp2(__builtin_fmaf(s[kb][i], SCL2, -mu));
;       s[kb][i] = pv;
;       rs += pv;
;     }
;   rs = xsum32(rs);
;   l = l * alpha + rs;
;   if (__ballot(mn > m) != 0ull) {
; #pragma unroll
;     for (int db = 0; db < 2; ++db)
; #pragma unroll
;       for (int i = 0; i < 16; ++i) o[db][i] *= alpha;
;   }
;   m = mn;
; }
	s_nop 1
	v_cndmask_b32_e32 v137, v204, v87, vcc
	v_cmp_ne_u32_e32 vcc, 0, v138
	v_max3_f32 v99, v99, v136, v137
	s_nop 0
	v_cndmask_b32_e32 v138, v204, v88, vcc
	v_cmp_ne_u32_e32 vcc, 0, v139
	s_nop 1
	v_cndmask_b32_e32 v139, v204, v89, vcc
	v_cmp_ne_u32_e32 vcc, 0, v140
	v_max3_f32 v99, v99, v138, v139
	s_nop 0
	v_cndmask_b32_e32 v140, v204, v90, vcc
	v_cmp_ne_u32_e32 vcc, 0, v141
	s_nop 1
	v_cndmask_b32_e32 v141, v204, v91, vcc
	v_cmp_ne_u32_e32 vcc, 0, v142
	v_max3_f32 v99, v99, v140, v141
	s_nop 0
	v_cndmask_b32_e32 v142, v204, v92, vcc
	v_cmp_ne_u32_e32 vcc, 0, v143
	s_nop 1
	v_cndmask_b32_e32 v143, v204, v93, vcc
	v_cmp_ne_u32_e32 vcc, 0, v202
	v_max3_f32 v99, v99, v142, v143
	s_nop 0
	v_cndmask_b32_e32 v202, v204, v94, vcc
	v_cmp_gt_i32_e32 vcc, 0, v96
	s_nop 1
	v_cndmask_b32_e32 v229, v204, v95, vcc
	v_max3_f32 v96, v99, v202, v229
	v_mul_f32_e32 v96, 0x3e38aa3b, v96
	v_mov_b32_e32 v99, v96
	s_nop 1
	v_permlane32_swap_b32_e32 v96, v99
	v_max3_f32 v251, v249, v96, v99
	v_cmp_lt_f32_e32 vcc, s1, v251
	v_sub_f32_e32 v252, v249, v251
	s_nop 0
	v_cndmask_b32_e64 v253, v204, -v251, vcc
	v_fmamk_f32 v96, v97, 0x3e38aa3b, v253
	v_exp_f32_e32 v96, v96
	v_fmamk_f32 v97, v98, 0x3e38aa3b, v253
	v_exp_f32_e32 v97, v97
	v_fmamk_f32 v98, v100, 0x3e38aa3b, v253
	v_exp_f32_e32 v98, v98
	v_fmamk_f32 v99, v101, 0x3e38aa3b, v253
	v_exp_f32_e32 v99, v99
	v_add_f32_e32 v100, 0, v96
	v_add_f32_e32 v100, v97, v100
	v_add_f32_e32 v100, v98, v100
	v_add_f32_e32 v254, v99, v100
	v_fmamk_f32 v100, v102, 0x3e38aa3b, v253
	v_exp_f32_e32 v100, v100
	v_fmamk_f32 v101, v103, 0x3e38aa3b, v253
	v_exp_f32_e32 v101, v101
	v_fmamk_f32 v102, v104, 0x3e38aa3b, v253
	v_exp_f32_e32 v102, v102
	v_fmamk_f32 v103, v105, 0x3e38aa3b, v253
	v_exp_f32_e32 v103, v103
	v_add_f32_e32 v104, v100, v254
	v_add_f32_e32 v104, v101, v104
	v_add_f32_e32 v104, v102, v104
	v_add_f32_e32 v254, v103, v104
	v_fmamk_f32 v104, v106, 0x3e38aa3b, v253
	v_exp_f32_e32 v104, v104
	v_fmamk_f32 v105, v107, 0x3e38aa3b, v253
	v_exp_f32_e32 v105, v105
	v_fmamk_f32 v106, v108, 0x3e38aa3b, v253
	v_exp_f32_e32 v106, v106
	v_fmamk_f32 v107, v109, 0x3e38aa3b, v253
	v_exp_f32_e32 v107, v107
	v_add_f32_e32 v108, v104, v254
	v_add_f32_e32 v108, v105, v108
	v_add_f32_e32 v108, v106, v108
	v_add_f32_e32 v254, v107, v108
	v_fmamk_f32 v108, v110, 0x3e38aa3b, v253
	v_exp_f32_e32 v108, v108
	v_fmamk_f32 v109, v111, 0x3e38aa3b, v253
	v_exp_f32_e32 v109, v109
	v_fmamk_f32 v110, v128, 0x3e38aa3b, v253
	v_exp_f32_e32 v110, v110
	v_fmamk_f32 v111, v129, 0x3e38aa3b, v253
	v_exp_f32_e32 v111, v111
	v_add_f32_e32 v128, v108, v254
	v_add_f32_e32 v128, v109, v128
	v_add_f32_e32 v128, v110, v128
	v_add_f32_e32 v254, v111, v128
	v_fmamk_f32 v128, v130, 0x3e38aa3b, v253
	v_exp_f32_e32 v128, v128
	v_fmamk_f32 v129, v131, 0x3e38aa3b, v253
	v_exp_f32_e32 v129, v129
	v_fmamk_f32 v130, v132, 0x3e38aa3b, v253
	v_exp_f32_e32 v130, v130
	v_fmamk_f32 v131, v133, 0x3e38aa3b, v253
	v_exp_f32_e32 v131, v131
	v_add_f32_e32 v132, v128, v254
	v_add_f32_e32 v132, v129, v132
	v_add_f32_e32 v132, v130, v132
	v_add_f32_e32 v254, v131, v132
	v_fmamk_f32 v132, v134, 0x3e38aa3b, v253
	v_exp_f32_e32 v132, v132
	v_fmamk_f32 v133, v135, 0x3e38aa3b, v253
	v_exp_f32_e32 v133, v133
	v_fmamk_f32 v134, v136, 0x3e38aa3b, v253
	v_exp_f32_e32 v134, v134
	v_fmamk_f32 v135, v137, 0x3e38aa3b, v253
	v_exp_f32_e32 v135, v135
	v_add_f32_e32 v136, v132, v254
	v_add_f32_e32 v136, v133, v136
	v_add_f32_e32 v136, v134, v136
	v_add_f32_e32 v254, v135, v136
	v_fmamk_f32 v136, v138, 0x3e38aa3b, v253
	v_exp_f32_e32 v136, v136
	v_fmamk_f32 v137, v139, 0x3e38aa3b, v253
	v_exp_f32_e32 v137, v137
	v_fmamk_f32 v138, v140, 0x3e38aa3b, v253
	v_exp_f32_e32 v138, v138
	v_fmamk_f32 v139, v141, 0x3e38aa3b, v253
	v_exp_f32_e32 v139, v139
	v_add_f32_e32 v140, v136, v254
	v_add_f32_e32 v140, v137, v140
	v_add_f32_e32 v140, v138, v140
	v_add_f32_e32 v254, v139, v140
	v_fmamk_f32 v140, v142, 0x3e38aa3b, v253
	v_exp_f32_e32 v140, v140
	v_fmamk_f32 v141, v143, 0x3e38aa3b, v253
	v_exp_f32_e32 v141, v141
	v_fmamk_f32 v142, v202, 0x3e38aa3b, v253
	v_exp_f32_e32 v142, v142
	v_fmac_f32_e32 v253, 0x3e38aa3b, v229
	v_exp_f32_e32 v143, v253
	v_add_f32_e32 v202, v140, v254
	v_add_f32_e32 v202, v141, v202
	v_add_f32_e32 v202, v142, v202
	v_add_f32_e32 v229, v143, v202
	v_exp_f32_e32 v202, v252
	v_mov_b32_e32 v252, v229
	s_nop 1
	v_permlane32_swap_b32_e32 v229, v252
	v_cmp_gt_f32_e32 vcc, v251, v249
	v_add_f32_e32 v252, v229, v252
	s_cmp_lg_u64 vcc, 0
	v_fmac_f32_e32 v252, v248, v202
	s_cselect_b64 s[12:13], -1, 0
	s_cbranch_execnz .LBB0_1740

; #define MFMA32(a, b, c) __builtin_amdgcn_mfma_f32_32x32x16_bf16((a), (b), (c), 0, 0, 0)
; DI void pv_tile(const u16* Vs, const f32x16* s, f32x16* o, int rl, int hh) {
; #pragma unroll
;   for (int kk = 0; kk < 4; ++kk) {
;     const int kb = kk >> 1, i0 = 8 * (kk & 1);
;     bf16x8 pf = pack8(s[kb][i0], s[kb][i0 + 1], s[kb][i0 + 2], s[kb][i0 + 3], s[kb][i0 + 4], s[kb][i0 + 5], s[kb][i0 + 6], s[kb][i0 + 7]);
; #pragma unroll
;     for (int db = 0; db < 2; ++db) {
;       const u16* vp = Vs + (db * 32 + rl) * KVS + kk * 16 + hh * 4;
;       s16x4 lo = *(const s16x4*)vp, hi = *(const s16x4*)(vp + 8);
;       bf16x8 a = __builtin_shufflevector(lo, hi, 0, 1, 2, 3, 4, 5, 6, 7);
;       o[db] = MFMA32(a, pf, o[db]);
;     }
;   }
; }
.LBB0_1744:
	s_nop 0
	v_lshlrev_b32_e32 v84, 1, v246
	v_add3_u32 v88, v250, v247, v84
	s_nop 2
	v_add_u32_e32 v89, 0xf800, v88
	v_add_u32_e32 v88, 0x10800, v88
	ds_read2_b64 v[112:115], v89 offset0:128 offset1:130
	ds_read2_b64 v[116:119], v88 offset0:192 offset1:194
	ds_read2_b64 v[120:123], v89 offset0:132 offset1:134
	ds_read2_b64 v[124:127], v88 offset0:196 offset1:198
	ds_read2_b64 v[84:87], v89 offset0:136 offset1:138
	ds_read2_b64 v[92:95], v88 offset0:200 offset1:202
	v_cvt_pk_bf16_f32 v80, v96, v97
	v_cvt_pk_bf16_f32 v81, v98, v99
	v_cvt_pk_bf16_f32 v82, v100, v101
	v_cvt_pk_bf16_f32 v83, v102, v103
	s_nop 1
	ds_read2_b64 v[96:99], v89 offset0:140 offset1:142
	ds_read2_b64 v[100:103], v88 offset0:204 offset1:206
	v_mov_b32_e32 v248, v252
	v_mov_b32_e32 v249, v251
	s_waitcnt lgkmcnt(7)
	v_mfma_f32_32x32x16_bf16 v[64:79], v[112:115], v[80:83], v[64:79]
	s_waitcnt lgkmcnt(6)
	v_mfma_f32_32x32x16_bf16 v[48:63], v[116:119], v[80:83], v[48:63]
	v_cvt_pk_bf16_f32 v80, v104, v105
	v_cvt_pk_bf16_f32 v81, v106, v107
	v_cvt_pk_bf16_f32 v82, v108, v109
	v_cvt_pk_bf16_f32 v83, v110, v111
	s_nop 1
	s_waitcnt lgkmcnt(5)
	v_mfma_f32_32x32x16_bf16 v[64:79], v[120:123], v[80:83], v[64:79]
	s_waitcnt lgkmcnt(4)
	v_mfma_f32_32x32x16_bf16 v[48:63], v[124:127], v[80:83], v[48:63]
	v_cvt_pk_bf16_f32 v80, v128, v129
	v_cvt_pk_bf16_f32 v81, v130, v131
	v_cvt_pk_bf16_f32 v82, v132, v133
	v_cvt_pk_bf16_f32 v83, v134, v135
	s_nop 1
	s_waitcnt lgkmcnt(3)
	v_mfma_f32_32x32x16_bf16 v[64:79], v[84:87], v[80:83], v[64:79]
	s_waitcnt lgkmcnt(2)
	v_mfma_f32_32x32x16_bf16 v[48:63], v[92:95], v[80:83], v[48:63]
	v_cvt_pk_bf16_f32 v80, v136, v137
	v_cvt_pk_bf16_f32 v81, v138, v139
	v_cvt_pk_bf16_f32 v82, v140, v141
	v_cvt_pk_bf16_f32 v83, v142, v143
	s_nop 1
	s_waitcnt lgkmcnt(1)
	v_mfma_f32_32x32x16_bf16 v[64:79], v[96:99], v[80:83], v[64:79]
	s_waitcnt lgkmcnt(0)
	v_mfma_f32_32x32x16_bf16 v[48:63], v[100:103], v[80:83], v[48:63]
